# ffn_up epilogue store part: 8 LDS reads in flight, one 64-bit multiply then incremental store addresses
# speedup vs baseline: 1.0144x; 1.0035x over previous
; template <int MI, int NJ> ...
;     ...
;   for (int kt = 0; kt < nk; ++kt) {
;     const int buf = kt & 1;
;     {
;       G8STORE(buf ^ 1);
;       const u16* ga_ = (kt + 2 < nk) ? Ag + (kt + 2) * 64 : Ag + nAoff;
;       const u16* gb_ = (kt + 2 < nk) ? Bg + (kt + 2) * 64 : Bg + nBoff;
;       G8LOADP(ga_, gb_);
;     }
;     __builtin_amdgcn_sched_barrier(0);
;     __builtin_amdgcn_s_setprio(1);
;     const u16* a = ra_ + buf * AROWS * 64;
;     const u16* b = rb_ + buf * BROWS * 64;
; #pragma unroll
;     for (int ks = 0; ks < 2; ++ks) {
;       const u16* a_ = ks ? a + dsw : a;
;       const u16* b_ = ks ? b + dsw : b;
;       bf16x8 bfr[NJ];
; #pragma unroll
;       for (int j = 0; j < NJ; ++j) bfr[j] = *(const bf16x8*)(b_ + j * 16 * 64);
; #pragma unroll
;       for (int ih = 0; ih < MI / 4; ++ih) {
;         bf16x8 af[4];
; #pragma unroll
;         for (int i = 0; i < 4; ++i) af[i] = *(const bf16x8*)(a_ + (ih * 4 + i) * 16 * 64);
; #pragma unroll
;         for (int i = 0; i < 4; ++i)
; #pragma unroll
;           for (int j = 0; j < NJ; ++j) acc[ih * 4 + i][j] = mfma16(af[i], bfr[j], acc[ih * 4 + i][j]);
;       }
;     }
;     __builtin_amdgcn_s_setprio(0);
;     __builtin_amdgcn_sched_barrier(0);
;     __syncthreads();
;   }
.LBB0_601:
	s_setprio 1
	s_waitcnt lgkmcnt(6)
	v_mfma_f32_16x16x32_bf16 v[158:161], v[212:215], v[208:211], v[158:161]
	s_waitcnt lgkmcnt(5)
	v_mfma_f32_16x16x32_bf16 v[154:157], v[216:219], v[208:211], v[154:157]
	s_waitcnt lgkmcnt(4)
	v_mfma_f32_16x16x32_bf16 v[150:153], v[220:223], v[208:211], v[150:153]
	s_waitcnt lgkmcnt(3)
	v_mfma_f32_16x16x32_bf16 v[146:149], v[224:227], v[208:211], v[146:149]
	ds_read_b128 v[208:211], v228 offset:8192
	s_waitcnt lgkmcnt(3)
	v_mfma_f32_16x16x32_bf16 v[142:145], v[212:215], v[234:237], v[142:145]
	v_mfma_f32_16x16x32_bf16 v[138:141], v[216:219], v[234:237], v[138:141]
	v_mfma_f32_16x16x32_bf16 v[134:137], v[220:223], v[234:237], v[134:137]
	v_mfma_f32_16x16x32_bf16 v[130:133], v[224:227], v[234:237], v[130:133]
	ds_read_b128 v[234:237], v228 offset:10240
	s_waitcnt lgkmcnt(3)
	v_mfma_f32_16x16x32_bf16 v[126:129], v[212:215], v[238:241], v[126:129]
	v_mfma_f32_16x16x32_bf16 v[122:125], v[216:219], v[238:241], v[122:125]
	v_mfma_f32_16x16x32_bf16 v[118:121], v[220:223], v[238:241], v[118:121]
	v_mfma_f32_16x16x32_bf16 v[114:117], v[224:227], v[238:241], v[114:117]
	ds_read_b128 v[238:241], v228 offset:12288
	ds_read_b128 v[242:245], v229
	ds_read_b128 v[246:249], v229 offset:2048
	s_waitcnt lgkmcnt(5)
	v_mfma_f32_16x16x32_bf16 v[110:113], v[212:215], v[204:207], v[110:113]
	v_mfma_f32_16x16x32_bf16 v[106:109], v[216:219], v[204:207], v[106:109]
	v_mfma_f32_16x16x32_bf16 v[102:105], v[220:223], v[204:207], v[102:105]
	v_mfma_f32_16x16x32_bf16 v[98:101], v[224:227], v[204:207], v[98:101]
	ds_read_b128 v[204:207], v228 offset:14336
	ds_read_b128 v[190:193], v229 offset:4096
	ds_read_b128 v[170:173], v229 offset:6144
	s_waitcnt lgkmcnt(7)
	v_mfma_f32_16x16x32_bf16 v[94:97], v[212:215], v[208:211], v[94:97]
	v_mfma_f32_16x16x32_bf16 v[90:93], v[216:219], v[208:211], v[90:93]
	v_mfma_f32_16x16x32_bf16 v[86:89], v[220:223], v[208:211], v[86:89]
	v_mfma_f32_16x16x32_bf16 v[82:85], v[224:227], v[208:211], v[82:85]
	v_add_u32_e32 v228, v228, v196
	ds_read_b128 v[208:211], v228
	s_waitcnt vmcnt(7)
	ds_write_b128 v199, v[2:5]
	global_load_dwordx4 v[2:5], v169, s[50:51]
	s_waitcnt lgkmcnt(8)
	v_mfma_f32_16x16x32_bf16 v[78:81], v[212:215], v[234:237], v[78:81]
	v_mfma_f32_16x16x32_bf16 v[74:77], v[216:219], v[234:237], v[74:77]
	v_mfma_f32_16x16x32_bf16 v[70:73], v[220:223], v[234:237], v[70:73]
	v_mfma_f32_16x16x32_bf16 v[66:69], v[224:227], v[234:237], v[66:69]
	ds_read_b128 v[234:237], v228 offset:2048
	s_waitcnt vmcnt(7)
	ds_write_b128 v199, v[6:9] offset:8192
	global_load_dwordx4 v[6:9], v194, s[50:51]
	s_waitcnt lgkmcnt(9)
	v_mfma_f32_16x16x32_bf16 v[62:65], v[212:215], v[238:241], v[62:65]
	v_mfma_f32_16x16x32_bf16 v[58:61], v[216:219], v[238:241], v[58:61]
	v_mfma_f32_16x16x32_bf16 v[54:57], v[220:223], v[238:241], v[54:57]
	v_mfma_f32_16x16x32_bf16 v[50:53], v[224:227], v[238:241], v[50:53]
	ds_read_b128 v[238:241], v228 offset:4096
	s_waitcnt vmcnt(7)
	ds_write_b128 v199, v[10:13] offset:16384
	global_load_dwordx4 v[10:13], v195, s[50:51]
	s_waitcnt lgkmcnt(8)
	v_mfma_f32_16x16x32_bf16 v[46:49], v[212:215], v[204:207], v[46:49]
	v_mfma_f32_16x16x32_bf16 v[42:45], v[216:219], v[204:207], v[42:45]
	v_mfma_f32_16x16x32_bf16 v[38:41], v[220:223], v[204:207], v[38:41]
	v_mfma_f32_16x16x32_bf16 v[34:37], v[224:227], v[204:207], v[34:37]
	ds_read_b128 v[204:207], v228 offset:6144
	s_waitcnt vmcnt(7)
	ds_write_b128 v199, v[18:21] offset:24576
	global_load_dwordx4 v[18:21], v198, s[50:51]
	s_waitcnt lgkmcnt(7)
	v_mfma_f32_16x16x32_bf16 v[158:161], v[242:245], v[208:211], v[158:161]
	v_mfma_f32_16x16x32_bf16 v[154:157], v[246:249], v[208:211], v[154:157]
	v_mfma_f32_16x16x32_bf16 v[150:153], v[190:193], v[208:211], v[150:153]
	v_mfma_f32_16x16x32_bf16 v[146:149], v[170:173], v[208:211], v[146:149]
	ds_read_b128 v[208:211], v228 offset:8192
	s_waitcnt vmcnt(7)
	ds_write_b128 v200, v[14:17]
	global_load_dwordx4 v[14:17], v169, s[52:53]
	s_waitcnt lgkmcnt(7)
	v_mfma_f32_16x16x32_bf16 v[142:145], v[242:245], v[234:237], v[142:145]
	v_mfma_f32_16x16x32_bf16 v[138:141], v[246:249], v[234:237], v[138:141]
	v_mfma_f32_16x16x32_bf16 v[134:137], v[190:193], v[234:237], v[134:137]
	v_mfma_f32_16x16x32_bf16 v[130:133], v[170:173], v[234:237], v[130:133]
	ds_read_b128 v[234:237], v228 offset:10240
	s_waitcnt vmcnt(7)
	ds_write_b128 v200, v[22:25] offset:8192
	global_load_dwordx4 v[22:25], v194, s[52:53]
	s_waitcnt lgkmcnt(7)
	v_mfma_f32_16x16x32_bf16 v[126:129], v[242:245], v[238:241], v[126:129]
	v_mfma_f32_16x16x32_bf16 v[122:125], v[246:249], v[238:241], v[122:125]
	v_mfma_f32_16x16x32_bf16 v[118:121], v[190:193], v[238:241], v[118:121]
	v_mfma_f32_16x16x32_bf16 v[114:117], v[170:173], v[238:241], v[114:117]
	ds_read_b128 v[238:241], v228 offset:12288
	s_waitcnt vmcnt(7)
	ds_write_b128 v200, v[26:29] offset:16384
	global_load_dwordx4 v[26:29], v195, s[52:53]
	s_waitcnt lgkmcnt(7)
	v_mfma_f32_16x16x32_bf16 v[110:113], v[242:245], v[204:207], v[110:113]
	v_mfma_f32_16x16x32_bf16 v[106:109], v[246:249], v[204:207], v[106:109]
	v_mfma_f32_16x16x32_bf16 v[102:105], v[190:193], v[204:207], v[102:105]
	v_mfma_f32_16x16x32_bf16 v[98:101], v[170:173], v[204:207], v[98:101]
	ds_read_b128 v[204:207], v228 offset:14336
	s_waitcnt vmcnt(7)
	ds_write_b128 v200, v[30:33] offset:24576
	global_load_dwordx4 v[30:33], v198, s[52:53]
	s_waitcnt lgkmcnt(7)
	v_mfma_f32_16x16x32_bf16 v[94:97], v[242:245], v[208:211], v[94:97]
	v_mfma_f32_16x16x32_bf16 v[90:93], v[246:249], v[208:211], v[90:93]
	v_mfma_f32_16x16x32_bf16 v[86:89], v[190:193], v[208:211], v[86:89]
	v_mfma_f32_16x16x32_bf16 v[82:85], v[170:173], v[208:211], v[82:85]
	s_waitcnt lgkmcnt(0)
	s_setprio 0
	s_barrier
; __device__ __forceinline__ float siluf_(float x) { return x / (1.0f + __expf(-x)); }
; template <int MI, int NJ> ...
;     ...
;   for (int kt = 0; kt < nk; ++kt) {
;     const int buf = kt & 1;
;     {
;       G8STORE(buf ^ 1);
;       const u16* ga_ = (kt + 2 < nk) ? Ag + (kt + 2) * 64 : Ag + nAoff;
;       const u16* gb_ = (kt + 2 < nk) ? Bg + (kt + 2) * 64 : Bg + nBoff;
;       G8LOADP(ga_, gb_);
;     }
;     __builtin_amdgcn_sched_barrier(0);
;     __builtin_amdgcn_s_setprio(1);
;     const u16* a = ra_ + buf * AROWS * 64;
;     const u16* b = rb_ + buf * BROWS * 64;
; #pragma unroll
;     for (int ks = 0; ks < 2; ++ks) {
;       const u16* a_ = ks ? a + dsw : a;
;       const u16* b_ = ks ? b + dsw : b;
;       bf16x8 bfr[NJ];
; #pragma unroll
;       for (int j = 0; j < NJ; ++j) bfr[j] = *(const bf16x8*)(b_ + j * 16 * 64);
; #pragma unroll
;       for (int ih = 0; ih < MI / 4; ++ih) {
;         bf16x8 af[4];
; #pragma unroll
;         for (int i = 0; i < 4; ++i) af[i] = *(const bf16x8*)(a_ + (ih * 4 + i) * 16 * 64);
; #pragma unroll
;         for (int i = 0; i < 4; ++i)
; #pragma unroll
;           for (int j = 0; j < NJ; ++j) acc[ih * 4 + i][j] = mfma16(af[i], bfr[j], acc[ih * 4 + i][j]);
;       }
;     }
;     __builtin_amdgcn_s_setprio(0);
;     __builtin_amdgcn_sched_barrier(0);
;     __syncthreads();
;   }
; __device__ __forceinline__ void phase_ffn_up(const Params& p, const u16* Wgu, u16* smem, volatile LAS unsigned* vb_) {
;     ...
; #pragma unroll
;     for (int i = 0; i < 8; ++i)
; #pragma unroll
;       for (int jp = 0; jp < 2; ++jp) {
; #pragma unroll
;         for (int r = 0; r < 4; ++r) {
;           const float g = acc[i][2 * jp][r], u = acc[i][2 * jp + 1][r];
;           smem[(wm * 128 + i * 16 + (lane >> 4) * 4 + r) * 136 + (wn * 2 + jp) * 16 + (lane & 15)] = f2bf(siluf_(g) * u);
;         }
;         __builtin_amdgcn_sched_barrier(0);
;       }
	s_add_i32 s43, s43, 1
	s_add_u32 s22, s22, 64
	s_addc_u32 s23, s23, 0
	s_addk_i32 s42, 0x4000
	s_and_b32 s48, s42, 0x4000
	s_xor_b32 s44, s48, 0x4000
	s_lshl_b32 s44, s44, 1
	v_add_u32_e32 v199, s44, v185
	v_add_u32_e32 v200, s44, v186
	s_cmp_lt_u32 s43, 14
	s_cselect_b32 s45, s23, s13
	s_cselect_b32 s44, s22, s12
	s_cselect_b32 s47, s23, s21
	s_cselect_b32 s46, s22, s20
	s_lshl_b64 s[44:45], s[44:45], 1
	s_lshl_b64 s[46:47], s[46:47], 1
	s_add_u32 s50, s62, s44
	s_addc_u32 s51, s63, s45
	s_add_u32 s52, s64, s46
	s_addc_u32 s53, s65, s47
	s_lshl_b32 s44, s48, 1
	v_add_u32_e32 v228, s44, v187
	v_add_u32_e32 v229, s44, v188
	s_setprio 1
	ds_read_b128 v[212:215], v229
	ds_read_b128 v[208:211], v228
	ds_read_b128 v[216:219], v229 offset:2048
	ds_read_b128 v[220:223], v229 offset:4096
	ds_read_b128 v[224:227], v229 offset:6144
	v_mfma_f32_16x16x32_bf16 v[78:81], v[242:245], v[234:237], v[78:81]
	v_mfma_f32_16x16x32_bf16 v[74:77], v[246:249], v[234:237], v[74:77]
	v_mfma_f32_16x16x32_bf16 v[70:73], v[190:193], v[234:237], v[70:73]
	v_mfma_f32_16x16x32_bf16 v[66:69], v[170:173], v[234:237], v[66:69]
	ds_read_b128 v[234:237], v228 offset:2048
	v_mfma_f32_16x16x32_bf16 v[62:65], v[242:245], v[238:241], v[62:65]
	v_mfma_f32_16x16x32_bf16 v[58:61], v[246:249], v[238:241], v[58:61]
	v_mfma_f32_16x16x32_bf16 v[54:57], v[190:193], v[238:241], v[54:57]
	v_mfma_f32_16x16x32_bf16 v[50:53], v[170:173], v[238:241], v[50:53]
	ds_read_b128 v[238:241], v228 offset:4096
	v_mfma_f32_16x16x32_bf16 v[46:49], v[242:245], v[204:207], v[46:49]
	v_mfma_f32_16x16x32_bf16 v[42:45], v[246:249], v[204:207], v[42:45]
	v_mfma_f32_16x16x32_bf16 v[38:41], v[190:193], v[204:207], v[38:41]
	v_mfma_f32_16x16x32_bf16 v[34:37], v[170:173], v[204:207], v[34:37]
	ds_read_b128 v[204:207], v228 offset:6144
	v_add_u32_e32 v229, v229, v196
	s_setprio 0
	s_cmpk_lg_i32 s22, 0x480
	s_cbranch_scc1 .LBB0_601
	v_and_b32_e32 v228, 15, v175
	v_bfe_u32 v229, v175, 8, 1
	v_lshl_or_b32 v228, v229, 7, v228
	v_mul_u32_u24_e32 v228, 0x110, v228
	v_bfe_u32 v229, v175, 6, 2
	v_lshl_add_u32 v228, v229, 6, v228
	v_bfe_u32 v229, v175, 4, 2
	v_lshl_add_u32 v228, v229, 3, v228
	v_mov_b32_e32 v224, 0xbfb8aa3b
	v_mov_b32_e32 v226, 1.0
	v_pk_mul_f32 v[208:209], v[158:159], v[224:225] op_sel_hi:[1,0]
	v_pk_mul_f32 v[210:211], v[160:161], v[224:225] op_sel_hi:[1,0]
	v_pk_mul_f32 v[212:213], v[150:151], v[224:225] op_sel_hi:[1,0]
	v_pk_mul_f32 v[214:215], v[152:153], v[224:225] op_sel_hi:[1,0]
	v_min_f32_e32 v208, 0x42fc0000, v208
	v_min_f32_e32 v209, 0x42fc0000, v209
	v_min_f32_e32 v210, 0x42fc0000, v210
	v_min_f32_e32 v211, 0x42fc0000, v211
	v_min_f32_e32 v212, 0x42fc0000, v212
	v_min_f32_e32 v213, 0x42fc0000, v213
	v_min_f32_e32 v214, 0x42fc0000, v214
	v_min_f32_e32 v215, 0x42fc0000, v215
	v_exp_f32_e32 v208, v208
	v_exp_f32_e32 v209, v209
	v_exp_f32_e32 v210, v210
	v_exp_f32_e32 v211, v211
	v_exp_f32_e32 v212, v212
	v_exp_f32_e32 v213, v213
	v_exp_f32_e32 v214, v214
	v_exp_f32_e32 v215, v215
	v_pk_add_f32 v[208:209], v[208:209], v[226:227] op_sel_hi:[1,0]
	v_pk_add_f32 v[210:211], v[210:211], v[226:227] op_sel_hi:[1,0]
	v_pk_add_f32 v[212:213], v[212:213], v[226:227] op_sel_hi:[1,0]
	v_pk_add_f32 v[214:215], v[214:215], v[226:227] op_sel_hi:[1,0]
	v_rcp_f32_e32 v216, v208
	v_rcp_f32_e32 v217, v209
	v_rcp_f32_e32 v218, v210
	v_rcp_f32_e32 v219, v211
	v_rcp_f32_e32 v220, v212
	v_rcp_f32_e32 v221, v213
	v_rcp_f32_e32 v222, v214
	v_rcp_f32_e32 v223, v215
	v_pk_fma_f32 v[208:209], v[208:209], v[216:217], v[226:227] op_sel_hi:[1,1,0] neg_lo:[1,0,0] neg_hi:[1,0,0]
	v_pk_fma_f32 v[210:211], v[210:211], v[218:219], v[226:227] op_sel_hi:[1,1,0] neg_lo:[1,0,0] neg_hi:[1,0,0]
	v_pk_fma_f32 v[212:213], v[212:213], v[220:221], v[226:227] op_sel_hi:[1,1,0] neg_lo:[1,0,0] neg_hi:[1,0,0]
	v_pk_fma_f32 v[214:215], v[214:215], v[222:223], v[226:227] op_sel_hi:[1,1,0] neg_lo:[1,0,0] neg_hi:[1,0,0]
	v_pk_fma_f32 v[216:217], v[208:209], v[216:217], v[216:217]
	v_pk_fma_f32 v[218:219], v[210:211], v[218:219], v[218:219]
	v_pk_fma_f32 v[220:221], v[212:213], v[220:221], v[220:221]
	v_pk_fma_f32 v[222:223], v[214:215], v[222:223], v[222:223]
	v_pk_mul_f32 v[158:159], v[158:159], v[216:217]
	v_pk_mul_f32 v[160:161], v[160:161], v[218:219]
	v_pk_mul_f32 v[150:151], v[150:151], v[220:221]
	v_pk_mul_f32 v[152:153], v[152:153], v[222:223]
	v_pk_mul_f32 v[158:159], v[158:159], v[154:155]
	v_pk_mul_f32 v[160:161], v[160:161], v[156:157]
	v_pk_mul_f32 v[150:151], v[150:151], v[146:147]
	v_pk_mul_f32 v[152:153], v[152:153], v[148:149]
	v_cvt_pk_bf16_f32 v158, v158, v159
	v_cvt_pk_bf16_f32 v159, v160, v161
	v_cvt_pk_bf16_f32 v150, v150, v151
	v_cvt_pk_bf16_f32 v151, v152, v153
	ds_write_b64 v228, v[158:159]
	ds_write_b64 v228, v[150:151] offset:32
	v_pk_mul_f32 v[208:209], v[142:143], v[224:225] op_sel_hi:[1,0]
	v_pk_mul_f32 v[210:211], v[144:145], v[224:225] op_sel_hi:[1,0]
	v_pk_mul_f32 v[212:213], v[134:135], v[224:225] op_sel_hi:[1,0]
	v_pk_mul_f32 v[214:215], v[136:137], v[224:225] op_sel_hi:[1,0]
	v_min_f32_e32 v208, 0x42fc0000, v208
	v_min_f32_e32 v209, 0x42fc0000, v209
	v_min_f32_e32 v210, 0x42fc0000, v210
	v_min_f32_e32 v211, 0x42fc0000, v211
	v_min_f32_e32 v212, 0x42fc0000, v212
	v_min_f32_e32 v213, 0x42fc0000, v213
	v_min_f32_e32 v214, 0x42fc0000, v214
	v_min_f32_e32 v215, 0x42fc0000, v215
	v_exp_f32_e32 v208, v208
	v_exp_f32_e32 v209, v209
	v_exp_f32_e32 v210, v210
	v_exp_f32_e32 v211, v211
	v_exp_f32_e32 v212, v212
	v_exp_f32_e32 v213, v213
	v_exp_f32_e32 v214, v214
	v_exp_f32_e32 v215, v215
	v_pk_add_f32 v[208:209], v[208:209], v[226:227] op_sel_hi:[1,0]
	v_pk_add_f32 v[210:211], v[210:211], v[226:227] op_sel_hi:[1,0]
; __device__ __forceinline__ float siluf_(float x) { return x / (1.0f + __expf(-x)); }
; __device__ __forceinline__ void phase_ffn_up(const Params& p, const u16* Wgu, u16* smem, volatile LAS unsigned* vb_) {
;     ...
; #pragma unroll
;     for (int i = 0; i < 8; ++i)
; #pragma unroll
;       for (int jp = 0; jp < 2; ++jp) {
; #pragma unroll
;         for (int r = 0; r < 4; ++r) {
;           const float g = acc[i][2 * jp][r], u = acc[i][2 * jp + 1][r];
;           smem[(wm * 128 + i * 16 + (lane >> 4) * 4 + r) * 136 + (wn * 2 + jp) * 16 + (lane & 15)] = f2bf(siluf_(g) * u);
;         }
;         __builtin_amdgcn_sched_barrier(0);
;       }
	v_pk_add_f32 v[212:213], v[212:213], v[226:227] op_sel_hi:[1,0]
	v_pk_add_f32 v[214:215], v[214:215], v[226:227] op_sel_hi:[1,0]
	v_rcp_f32_e32 v216, v208
	v_rcp_f32_e32 v217, v209
	v_rcp_f32_e32 v218, v210
	v_rcp_f32_e32 v219, v211
	v_rcp_f32_e32 v220, v212
	v_rcp_f32_e32 v221, v213
	v_rcp_f32_e32 v222, v214
	v_rcp_f32_e32 v223, v215
	v_pk_fma_f32 v[208:209], v[208:209], v[216:217], v[226:227] op_sel_hi:[1,1,0] neg_lo:[1,0,0] neg_hi:[1,0,0]
	v_pk_fma_f32 v[210:211], v[210:211], v[218:219], v[226:227] op_sel_hi:[1,1,0] neg_lo:[1,0,0] neg_hi:[1,0,0]
	v_pk_fma_f32 v[212:213], v[212:213], v[220:221], v[226:227] op_sel_hi:[1,1,0] neg_lo:[1,0,0] neg_hi:[1,0,0]
	v_pk_fma_f32 v[214:215], v[214:215], v[222:223], v[226:227] op_sel_hi:[1,1,0] neg_lo:[1,0,0] neg_hi:[1,0,0]
	v_pk_fma_f32 v[216:217], v[208:209], v[216:217], v[216:217]
	v_pk_fma_f32 v[218:219], v[210:211], v[218:219], v[218:219]
	v_pk_fma_f32 v[220:221], v[212:213], v[220:221], v[220:221]
	v_pk_fma_f32 v[222:223], v[214:215], v[222:223], v[222:223]
	v_pk_mul_f32 v[142:143], v[142:143], v[216:217]
	v_pk_mul_f32 v[144:145], v[144:145], v[218:219]
	v_pk_mul_f32 v[134:135], v[134:135], v[220:221]
	v_pk_mul_f32 v[136:137], v[136:137], v[222:223]
	v_pk_mul_f32 v[142:143], v[142:143], v[138:139]
	v_pk_mul_f32 v[144:145], v[144:145], v[140:141]
	v_pk_mul_f32 v[134:135], v[134:135], v[130:131]
	v_pk_mul_f32 v[136:137], v[136:137], v[132:133]
	v_cvt_pk_bf16_f32 v142, v142, v143
	v_cvt_pk_bf16_f32 v143, v144, v145
	v_cvt_pk_bf16_f32 v134, v134, v135
	v_cvt_pk_bf16_f32 v135, v136, v137
	ds_write_b64 v228, v[142:143] offset:4352
	ds_write_b64 v228, v[134:135] offset:4384
	v_pk_mul_f32 v[208:209], v[126:127], v[224:225] op_sel_hi:[1,0]
	v_pk_mul_f32 v[210:211], v[128:129], v[224:225] op_sel_hi:[1,0]
	v_pk_mul_f32 v[212:213], v[118:119], v[224:225] op_sel_hi:[1,0]
	v_pk_mul_f32 v[214:215], v[120:121], v[224:225] op_sel_hi:[1,0]
	v_min_f32_e32 v208, 0x42fc0000, v208
	v_min_f32_e32 v209, 0x42fc0000, v209
	v_min_f32_e32 v210, 0x42fc0000, v210
	v_min_f32_e32 v211, 0x42fc0000, v211
	v_min_f32_e32 v212, 0x42fc0000, v212
	v_min_f32_e32 v213, 0x42fc0000, v213
	v_min_f32_e32 v214, 0x42fc0000, v214
	v_min_f32_e32 v215, 0x42fc0000, v215
	v_exp_f32_e32 v208, v208
	v_exp_f32_e32 v209, v209
	v_exp_f32_e32 v210, v210
	v_exp_f32_e32 v211, v211
	v_exp_f32_e32 v212, v212
	v_exp_f32_e32 v213, v213
	v_exp_f32_e32 v214, v214
	v_exp_f32_e32 v215, v215
	v_pk_add_f32 v[208:209], v[208:209], v[226:227] op_sel_hi:[1,0]
	v_pk_add_f32 v[210:211], v[210:211], v[226:227] op_sel_hi:[1,0]
	v_pk_add_f32 v[212:213], v[212:213], v[226:227] op_sel_hi:[1,0]
	v_pk_add_f32 v[214:215], v[214:215], v[226:227] op_sel_hi:[1,0]
	v_rcp_f32_e32 v216, v208
	v_rcp_f32_e32 v217, v209
	v_rcp_f32_e32 v218, v210
	v_rcp_f32_e32 v219, v211
	v_rcp_f32_e32 v220, v212
	v_rcp_f32_e32 v221, v213
	v_rcp_f32_e32 v222, v214
	v_rcp_f32_e32 v223, v215
	v_pk_fma_f32 v[208:209], v[208:209], v[216:217], v[226:227] op_sel_hi:[1,1,0] neg_lo:[1,0,0] neg_hi:[1,0,0]
	v_pk_fma_f32 v[210:211], v[210:211], v[218:219], v[226:227] op_sel_hi:[1,1,0] neg_lo:[1,0,0] neg_hi:[1,0,0]
	v_pk_fma_f32 v[212:213], v[212:213], v[220:221], v[226:227] op_sel_hi:[1,1,0] neg_lo:[1,0,0] neg_hi:[1,0,0]
	v_pk_fma_f32 v[214:215], v[214:215], v[222:223], v[226:227] op_sel_hi:[1,1,0] neg_lo:[1,0,0] neg_hi:[1,0,0]
	v_pk_fma_f32 v[216:217], v[208:209], v[216:217], v[216:217]
	v_pk_fma_f32 v[218:219], v[210:211], v[218:219], v[218:219]
	v_pk_fma_f32 v[220:221], v[212:213], v[220:221], v[220:221]
	v_pk_fma_f32 v[222:223], v[214:215], v[222:223], v[222:223]
	v_pk_mul_f32 v[126:127], v[126:127], v[216:217]
	v_pk_mul_f32 v[128:129], v[128:129], v[218:219]
	v_pk_mul_f32 v[118:119], v[118:119], v[220:221]
	v_pk_mul_f32 v[120:121], v[120:121], v[222:223]
	v_pk_mul_f32 v[126:127], v[126:127], v[122:123]
	v_pk_mul_f32 v[128:129], v[128:129], v[124:125]
	v_pk_mul_f32 v[118:119], v[118:119], v[114:115]
	v_pk_mul_f32 v[120:121], v[120:121], v[116:117]
	v_cvt_pk_bf16_f32 v126, v126, v127
	v_cvt_pk_bf16_f32 v127, v128, v129
	v_cvt_pk_bf16_f32 v118, v118, v119
	v_cvt_pk_bf16_f32 v119, v120, v121
	ds_write_b64 v228, v[126:127] offset:8704
	ds_write_b64 v228, v[118:119] offset:8736
	v_pk_mul_f32 v[208:209], v[110:111], v[224:225] op_sel_hi:[1,0]
	v_pk_mul_f32 v[210:211], v[112:113], v[224:225] op_sel_hi:[1,0]
	v_pk_mul_f32 v[212:213], v[102:103], v[224:225] op_sel_hi:[1,0]
	v_pk_mul_f32 v[214:215], v[104:105], v[224:225] op_sel_hi:[1,0]
	v_min_f32_e32 v208, 0x42fc0000, v208
	v_min_f32_e32 v209, 0x42fc0000, v209
	v_min_f32_e32 v210, 0x42fc0000, v210
	v_min_f32_e32 v211, 0x42fc0000, v211
	v_min_f32_e32 v212, 0x42fc0000, v212
	v_min_f32_e32 v213, 0x42fc0000, v213
	v_min_f32_e32 v214, 0x42fc0000, v214
	v_min_f32_e32 v215, 0x42fc0000, v215
	v_exp_f32_e32 v208, v208
	v_exp_f32_e32 v209, v209
	v_exp_f32_e32 v210, v210
	v_exp_f32_e32 v211, v211
	v_exp_f32_e32 v212, v212
	v_exp_f32_e32 v213, v213
	v_exp_f32_e32 v214, v214
	v_exp_f32_e32 v215, v215
	v_pk_add_f32 v[208:209], v[208:209], v[226:227] op_sel_hi:[1,0]
	v_pk_add_f32 v[210:211], v[210:211], v[226:227] op_sel_hi:[1,0]
	v_pk_add_f32 v[212:213], v[212:213], v[226:227] op_sel_hi:[1,0]
	v_pk_add_f32 v[214:215], v[214:215], v[226:227] op_sel_hi:[1,0]
	v_rcp_f32_e32 v216, v208
	v_rcp_f32_e32 v217, v209
	v_rcp_f32_e32 v218, v210
	v_rcp_f32_e32 v219, v211
	v_rcp_f32_e32 v220, v212
	v_rcp_f32_e32 v221, v213
	v_rcp_f32_e32 v222, v214
	v_rcp_f32_e32 v223, v215
	v_pk_fma_f32 v[208:209], v[208:209], v[216:217], v[226:227] op_sel_hi:[1,1,0] neg_lo:[1,0,0] neg_hi:[1,0,0]
	v_pk_fma_f32 v[210:211], v[210:211], v[218:219], v[226:227] op_sel_hi:[1,1,0] neg_lo:[1,0,0] neg_hi:[1,0,0]
; __device__ __forceinline__ float siluf_(float x) { return x / (1.0f + __expf(-x)); }
; __device__ __forceinline__ void phase_ffn_up(const Params& p, const u16* Wgu, u16* smem, volatile LAS unsigned* vb_) {
;     ...
; #pragma unroll
;     for (int i = 0; i < 8; ++i)
; #pragma unroll
;       for (int jp = 0; jp < 2; ++jp) {
; #pragma unroll
;         for (int r = 0; r < 4; ++r) {
;           const float g = acc[i][2 * jp][r], u = acc[i][2 * jp + 1][r];
;           smem[(wm * 128 + i * 16 + (lane >> 4) * 4 + r) * 136 + (wn * 2 + jp) * 16 + (lane & 15)] = f2bf(siluf_(g) * u);
;         }
;         __builtin_amdgcn_sched_barrier(0);
;       }
	v_pk_fma_f32 v[212:213], v[212:213], v[220:221], v[226:227] op_sel_hi:[1,1,0] neg_lo:[1,0,0] neg_hi:[1,0,0]
	v_pk_fma_f32 v[214:215], v[214:215], v[222:223], v[226:227] op_sel_hi:[1,1,0] neg_lo:[1,0,0] neg_hi:[1,0,0]
	v_pk_fma_f32 v[216:217], v[208:209], v[216:217], v[216:217]
	v_pk_fma_f32 v[218:219], v[210:211], v[218:219], v[218:219]
	v_pk_fma_f32 v[220:221], v[212:213], v[220:221], v[220:221]
	v_pk_fma_f32 v[222:223], v[214:215], v[222:223], v[222:223]
	v_pk_mul_f32 v[110:111], v[110:111], v[216:217]
	v_pk_mul_f32 v[112:113], v[112:113], v[218:219]
	v_pk_mul_f32 v[102:103], v[102:103], v[220:221]
	v_pk_mul_f32 v[104:105], v[104:105], v[222:223]
	v_pk_mul_f32 v[110:111], v[110:111], v[106:107]
	v_pk_mul_f32 v[112:113], v[112:113], v[108:109]
	v_pk_mul_f32 v[102:103], v[102:103], v[98:99]
	v_pk_mul_f32 v[104:105], v[104:105], v[100:101]
	v_cvt_pk_bf16_f32 v110, v110, v111
	v_cvt_pk_bf16_f32 v111, v112, v113
	v_cvt_pk_bf16_f32 v102, v102, v103
	v_cvt_pk_bf16_f32 v103, v104, v105
	ds_write_b64 v228, v[110:111] offset:13056
	ds_write_b64 v228, v[102:103] offset:13088
	v_pk_mul_f32 v[208:209], v[94:95], v[224:225] op_sel_hi:[1,0]
	v_pk_mul_f32 v[210:211], v[96:97], v[224:225] op_sel_hi:[1,0]
	v_pk_mul_f32 v[212:213], v[86:87], v[224:225] op_sel_hi:[1,0]
	v_pk_mul_f32 v[214:215], v[88:89], v[224:225] op_sel_hi:[1,0]
	v_min_f32_e32 v208, 0x42fc0000, v208
	v_min_f32_e32 v209, 0x42fc0000, v209
	v_min_f32_e32 v210, 0x42fc0000, v210
	v_min_f32_e32 v211, 0x42fc0000, v211
	v_min_f32_e32 v212, 0x42fc0000, v212
	v_min_f32_e32 v213, 0x42fc0000, v213
	v_min_f32_e32 v214, 0x42fc0000, v214
	v_min_f32_e32 v215, 0x42fc0000, v215
	v_exp_f32_e32 v208, v208
	v_exp_f32_e32 v209, v209
	v_exp_f32_e32 v210, v210
	v_exp_f32_e32 v211, v211
	v_exp_f32_e32 v212, v212
	v_exp_f32_e32 v213, v213
	v_exp_f32_e32 v214, v214
	v_exp_f32_e32 v215, v215
	v_pk_add_f32 v[208:209], v[208:209], v[226:227] op_sel_hi:[1,0]
	v_pk_add_f32 v[210:211], v[210:211], v[226:227] op_sel_hi:[1,0]
	v_pk_add_f32 v[212:213], v[212:213], v[226:227] op_sel_hi:[1,0]
	v_pk_add_f32 v[214:215], v[214:215], v[226:227] op_sel_hi:[1,0]
	v_rcp_f32_e32 v216, v208
	v_rcp_f32_e32 v217, v209
	v_rcp_f32_e32 v218, v210
	v_rcp_f32_e32 v219, v211
	v_rcp_f32_e32 v220, v212
	v_rcp_f32_e32 v221, v213
	v_rcp_f32_e32 v222, v214
	v_rcp_f32_e32 v223, v215
	v_pk_fma_f32 v[208:209], v[208:209], v[216:217], v[226:227] op_sel_hi:[1,1,0] neg_lo:[1,0,0] neg_hi:[1,0,0]
	v_pk_fma_f32 v[210:211], v[210:211], v[218:219], v[226:227] op_sel_hi:[1,1,0] neg_lo:[1,0,0] neg_hi:[1,0,0]
	v_pk_fma_f32 v[212:213], v[212:213], v[220:221], v[226:227] op_sel_hi:[1,1,0] neg_lo:[1,0,0] neg_hi:[1,0,0]
	v_pk_fma_f32 v[214:215], v[214:215], v[222:223], v[226:227] op_sel_hi:[1,1,0] neg_lo:[1,0,0] neg_hi:[1,0,0]
	v_pk_fma_f32 v[216:217], v[208:209], v[216:217], v[216:217]
	v_pk_fma_f32 v[218:219], v[210:211], v[218:219], v[218:219]
	v_pk_fma_f32 v[220:221], v[212:213], v[220:221], v[220:221]
	v_pk_fma_f32 v[222:223], v[214:215], v[222:223], v[222:223]
	v_pk_mul_f32 v[94:95], v[94:95], v[216:217]
	v_pk_mul_f32 v[96:97], v[96:97], v[218:219]
	v_pk_mul_f32 v[86:87], v[86:87], v[220:221]
	v_pk_mul_f32 v[88:89], v[88:89], v[222:223]
	v_pk_mul_f32 v[94:95], v[94:95], v[90:91]
	v_pk_mul_f32 v[96:97], v[96:97], v[92:93]
	v_pk_mul_f32 v[86:87], v[86:87], v[82:83]
	v_pk_mul_f32 v[88:89], v[88:89], v[84:85]
	v_cvt_pk_bf16_f32 v94, v94, v95
	v_cvt_pk_bf16_f32 v95, v96, v97
	v_cvt_pk_bf16_f32 v86, v86, v87
	v_cvt_pk_bf16_f32 v87, v88, v89
	ds_write_b64 v228, v[94:95] offset:17408
	ds_write_b64 v228, v[86:87] offset:17440
	v_pk_mul_f32 v[208:209], v[78:79], v[224:225] op_sel_hi:[1,0]
	v_pk_mul_f32 v[210:211], v[80:81], v[224:225] op_sel_hi:[1,0]
	v_pk_mul_f32 v[212:213], v[70:71], v[224:225] op_sel_hi:[1,0]
	v_pk_mul_f32 v[214:215], v[72:73], v[224:225] op_sel_hi:[1,0]
	v_min_f32_e32 v208, 0x42fc0000, v208
	v_min_f32_e32 v209, 0x42fc0000, v209
	v_min_f32_e32 v210, 0x42fc0000, v210
	v_min_f32_e32 v211, 0x42fc0000, v211
	v_min_f32_e32 v212, 0x42fc0000, v212
	v_min_f32_e32 v213, 0x42fc0000, v213
	v_min_f32_e32 v214, 0x42fc0000, v214
	v_min_f32_e32 v215, 0x42fc0000, v215
	v_exp_f32_e32 v208, v208
	v_exp_f32_e32 v209, v209
	v_exp_f32_e32 v210, v210
	v_exp_f32_e32 v211, v211
	v_exp_f32_e32 v212, v212
	v_exp_f32_e32 v213, v213
	v_exp_f32_e32 v214, v214
	v_exp_f32_e32 v215, v215
	v_pk_add_f32 v[208:209], v[208:209], v[226:227] op_sel_hi:[1,0]
	v_pk_add_f32 v[210:211], v[210:211], v[226:227] op_sel_hi:[1,0]
	v_pk_add_f32 v[212:213], v[212:213], v[226:227] op_sel_hi:[1,0]
	v_pk_add_f32 v[214:215], v[214:215], v[226:227] op_sel_hi:[1,0]
	v_rcp_f32_e32 v216, v208
	v_rcp_f32_e32 v217, v209
	v_rcp_f32_e32 v218, v210
	v_rcp_f32_e32 v219, v211
	v_rcp_f32_e32 v220, v212
	v_rcp_f32_e32 v221, v213
	v_rcp_f32_e32 v222, v214
	v_rcp_f32_e32 v223, v215
	v_pk_fma_f32 v[208:209], v[208:209], v[216:217], v[226:227] op_sel_hi:[1,1,0] neg_lo:[1,0,0] neg_hi:[1,0,0]
	v_pk_fma_f32 v[210:211], v[210:211], v[218:219], v[226:227] op_sel_hi:[1,1,0] neg_lo:[1,0,0] neg_hi:[1,0,0]
	v_pk_fma_f32 v[212:213], v[212:213], v[220:221], v[226:227] op_sel_hi:[1,1,0] neg_lo:[1,0,0] neg_hi:[1,0,0]
	v_pk_fma_f32 v[214:215], v[214:215], v[222:223], v[226:227] op_sel_hi:[1,1,0] neg_lo:[1,0,0] neg_hi:[1,0,0]
	v_pk_fma_f32 v[216:217], v[208:209], v[216:217], v[216:217]
	v_pk_fma_f32 v[218:219], v[210:211], v[218:219], v[218:219]
	v_pk_fma_f32 v[220:221], v[212:213], v[220:221], v[220:221]
	v_pk_fma_f32 v[222:223], v[214:215], v[222:223], v[222:223]
	v_pk_mul_f32 v[78:79], v[78:79], v[216:217]
	v_pk_mul_f32 v[80:81], v[80:81], v[218:219]
	v_pk_mul_f32 v[70:71], v[70:71], v[220:221]
	v_pk_mul_f32 v[72:73], v[72:73], v[222:223]
; __device__ __forceinline__ float siluf_(float x) { return x / (1.0f + __expf(-x)); }
; __device__ __forceinline__ void phase_ffn_up(const Params& p, const u16* Wgu, u16* smem, volatile LAS unsigned* vb_) {
;     ...
; #pragma unroll
;     for (int i = 0; i < 8; ++i)
; #pragma unroll
;       for (int jp = 0; jp < 2; ++jp) {
; #pragma unroll
;         for (int r = 0; r < 4; ++r) {
;           const float g = acc[i][2 * jp][r], u = acc[i][2 * jp + 1][r];
;           smem[(wm * 128 + i * 16 + (lane >> 4) * 4 + r) * 136 + (wn * 2 + jp) * 16 + (lane & 15)] = f2bf(siluf_(g) * u);
;         }
;         __builtin_amdgcn_sched_barrier(0);
;       }
;     __syncthreads();
; #pragma unroll
;     for (int k = 0; k < 8; ++k) {
;       const int c = tid + 512 * k;
;       const int row = c >> 4, ch = c & 15;
;       const uint4 v = *(const uint4*)(smem + row * 136 + ch * 8);
;       *(uint4*)(act + (size_t)(mt * 256 + row) * DFF + nt * 128 + ch * 8) = v;
;     }
;     __syncthreads();
	v_pk_mul_f32 v[78:79], v[78:79], v[74:75]
	v_pk_mul_f32 v[80:81], v[80:81], v[76:77]
	v_pk_mul_f32 v[70:71], v[70:71], v[66:67]
	v_pk_mul_f32 v[72:73], v[72:73], v[68:69]
	v_cvt_pk_bf16_f32 v78, v78, v79
	v_cvt_pk_bf16_f32 v79, v80, v81
	v_cvt_pk_bf16_f32 v70, v70, v71
	v_cvt_pk_bf16_f32 v71, v72, v73
	ds_write_b64 v228, v[78:79] offset:21760
	ds_write_b64 v228, v[70:71] offset:21792
	v_pk_mul_f32 v[208:209], v[62:63], v[224:225] op_sel_hi:[1,0]
	v_pk_mul_f32 v[210:211], v[64:65], v[224:225] op_sel_hi:[1,0]
	v_pk_mul_f32 v[212:213], v[54:55], v[224:225] op_sel_hi:[1,0]
	v_pk_mul_f32 v[214:215], v[56:57], v[224:225] op_sel_hi:[1,0]
	v_min_f32_e32 v208, 0x42fc0000, v208
	v_min_f32_e32 v209, 0x42fc0000, v209
	v_min_f32_e32 v210, 0x42fc0000, v210
	v_min_f32_e32 v211, 0x42fc0000, v211
	v_min_f32_e32 v212, 0x42fc0000, v212
	v_min_f32_e32 v213, 0x42fc0000, v213
	v_min_f32_e32 v214, 0x42fc0000, v214
	v_min_f32_e32 v215, 0x42fc0000, v215
	v_exp_f32_e32 v208, v208
	v_exp_f32_e32 v209, v209
	v_exp_f32_e32 v210, v210
	v_exp_f32_e32 v211, v211
	v_exp_f32_e32 v212, v212
	v_exp_f32_e32 v213, v213
	v_exp_f32_e32 v214, v214
	v_exp_f32_e32 v215, v215
	v_pk_add_f32 v[208:209], v[208:209], v[226:227] op_sel_hi:[1,0]
	v_pk_add_f32 v[210:211], v[210:211], v[226:227] op_sel_hi:[1,0]
	v_pk_add_f32 v[212:213], v[212:213], v[226:227] op_sel_hi:[1,0]
	v_pk_add_f32 v[214:215], v[214:215], v[226:227] op_sel_hi:[1,0]
	v_rcp_f32_e32 v216, v208
	v_rcp_f32_e32 v217, v209
	v_rcp_f32_e32 v218, v210
	v_rcp_f32_e32 v219, v211
	v_rcp_f32_e32 v220, v212
	v_rcp_f32_e32 v221, v213
	v_rcp_f32_e32 v222, v214
	v_rcp_f32_e32 v223, v215
	v_pk_fma_f32 v[208:209], v[208:209], v[216:217], v[226:227] op_sel_hi:[1,1,0] neg_lo:[1,0,0] neg_hi:[1,0,0]
	v_pk_fma_f32 v[210:211], v[210:211], v[218:219], v[226:227] op_sel_hi:[1,1,0] neg_lo:[1,0,0] neg_hi:[1,0,0]
	v_pk_fma_f32 v[212:213], v[212:213], v[220:221], v[226:227] op_sel_hi:[1,1,0] neg_lo:[1,0,0] neg_hi:[1,0,0]
	v_pk_fma_f32 v[214:215], v[214:215], v[222:223], v[226:227] op_sel_hi:[1,1,0] neg_lo:[1,0,0] neg_hi:[1,0,0]
	v_pk_fma_f32 v[216:217], v[208:209], v[216:217], v[216:217]
	v_pk_fma_f32 v[218:219], v[210:211], v[218:219], v[218:219]
	v_pk_fma_f32 v[220:221], v[212:213], v[220:221], v[220:221]
	v_pk_fma_f32 v[222:223], v[214:215], v[222:223], v[222:223]
	v_pk_mul_f32 v[62:63], v[62:63], v[216:217]
	v_pk_mul_f32 v[64:65], v[64:65], v[218:219]
	v_pk_mul_f32 v[54:55], v[54:55], v[220:221]
	v_pk_mul_f32 v[56:57], v[56:57], v[222:223]
	v_pk_mul_f32 v[62:63], v[62:63], v[58:59]
	v_pk_mul_f32 v[64:65], v[64:65], v[60:61]
	v_pk_mul_f32 v[54:55], v[54:55], v[50:51]
	v_pk_mul_f32 v[56:57], v[56:57], v[52:53]
	v_cvt_pk_bf16_f32 v62, v62, v63
	v_cvt_pk_bf16_f32 v63, v64, v65
	v_cvt_pk_bf16_f32 v54, v54, v55
	v_cvt_pk_bf16_f32 v55, v56, v57
	ds_write_b64 v228, v[62:63] offset:26112
	ds_write_b64 v228, v[54:55] offset:26144
	v_pk_mul_f32 v[208:209], v[46:47], v[224:225] op_sel_hi:[1,0]
	v_pk_mul_f32 v[210:211], v[48:49], v[224:225] op_sel_hi:[1,0]
	v_pk_mul_f32 v[212:213], v[38:39], v[224:225] op_sel_hi:[1,0]
	v_pk_mul_f32 v[214:215], v[40:41], v[224:225] op_sel_hi:[1,0]
	v_min_f32_e32 v208, 0x42fc0000, v208
	v_min_f32_e32 v209, 0x42fc0000, v209
	v_min_f32_e32 v210, 0x42fc0000, v210
	v_min_f32_e32 v211, 0x42fc0000, v211
	v_min_f32_e32 v212, 0x42fc0000, v212
	v_min_f32_e32 v213, 0x42fc0000, v213
	v_min_f32_e32 v214, 0x42fc0000, v214
	v_min_f32_e32 v215, 0x42fc0000, v215
	v_exp_f32_e32 v208, v208
	v_exp_f32_e32 v209, v209
	v_exp_f32_e32 v210, v210
	v_exp_f32_e32 v211, v211
	v_exp_f32_e32 v212, v212
	v_exp_f32_e32 v213, v213
	v_exp_f32_e32 v214, v214
	v_exp_f32_e32 v215, v215
	v_pk_add_f32 v[208:209], v[208:209], v[226:227] op_sel_hi:[1,0]
	v_pk_add_f32 v[210:211], v[210:211], v[226:227] op_sel_hi:[1,0]
	v_pk_add_f32 v[212:213], v[212:213], v[226:227] op_sel_hi:[1,0]
	v_pk_add_f32 v[214:215], v[214:215], v[226:227] op_sel_hi:[1,0]
	v_rcp_f32_e32 v216, v208
	v_rcp_f32_e32 v217, v209
	v_rcp_f32_e32 v218, v210
	v_rcp_f32_e32 v219, v211
	v_rcp_f32_e32 v220, v212
	v_rcp_f32_e32 v221, v213
	v_rcp_f32_e32 v222, v214
	v_rcp_f32_e32 v223, v215
	v_pk_fma_f32 v[208:209], v[208:209], v[216:217], v[226:227] op_sel_hi:[1,1,0] neg_lo:[1,0,0] neg_hi:[1,0,0]
	v_pk_fma_f32 v[210:211], v[210:211], v[218:219], v[226:227] op_sel_hi:[1,1,0] neg_lo:[1,0,0] neg_hi:[1,0,0]
	v_pk_fma_f32 v[212:213], v[212:213], v[220:221], v[226:227] op_sel_hi:[1,1,0] neg_lo:[1,0,0] neg_hi:[1,0,0]
	v_pk_fma_f32 v[214:215], v[214:215], v[222:223], v[226:227] op_sel_hi:[1,1,0] neg_lo:[1,0,0] neg_hi:[1,0,0]
	v_pk_fma_f32 v[216:217], v[208:209], v[216:217], v[216:217]
	v_pk_fma_f32 v[218:219], v[210:211], v[218:219], v[218:219]
	v_pk_fma_f32 v[220:221], v[212:213], v[220:221], v[220:221]
	v_pk_fma_f32 v[222:223], v[214:215], v[222:223], v[222:223]
	v_pk_mul_f32 v[46:47], v[46:47], v[216:217]
	v_pk_mul_f32 v[48:49], v[48:49], v[218:219]
	v_pk_mul_f32 v[38:39], v[38:39], v[220:221]
	v_pk_mul_f32 v[40:41], v[40:41], v[222:223]
	v_pk_mul_f32 v[46:47], v[46:47], v[42:43]
	v_pk_mul_f32 v[48:49], v[48:49], v[44:45]
	v_pk_mul_f32 v[38:39], v[38:39], v[34:35]
	v_pk_mul_f32 v[40:41], v[40:41], v[36:37]
	v_cvt_pk_bf16_f32 v46, v46, v47
	v_cvt_pk_bf16_f32 v47, v48, v49
	v_cvt_pk_bf16_f32 v38, v38, v39
	v_cvt_pk_bf16_f32 v39, v40, v41
	ds_write_b64 v228, v[46:47] offset:30464
	ds_write_b64 v228, v[38:39] offset:30496
	s_waitcnt lgkmcnt(0)
	s_barrier
	s_lshl_b32 s12, s40, 7
	s_ashr_i32 s13, s12, 31
	v_lshl_add_u64 v[38:39], s[12:13], 1, v[166:167]
	s_and_b64 vcc, exec, s[10:11]
	s_mov_b32 s20, s41
	ds_read_b128 v[42:45], v197
	ds_read_b128 v[46:49], v197 offset:8704
	ds_read_b128 v[50:53], v197 offset:17408
	ds_read_b128 v[54:57], v197 offset:26112
	ds_read_b128 v[58:61], v197 offset:34816
	ds_read_b128 v[62:65], v197 offset:43520
	ds_read_b128 v[66:69], v197 offset:52224
	ds_read_b128 v[70:73], v197 offset:60928
	v_add_u32_e32 v40, s39, v189
	v_mad_i64_i32 v[40:41], s[12:13], v40, s7, v[38:39]
	s_lshl_b32 s48, s7, 5
	s_mov_b32 s49, 0
	s_waitcnt lgkmcnt(7)
	global_store_dwordx4 v[40:41], v[42:45], off
	v_lshl_add_u64 v[40:41], v[40:41], 0, s[48:49]
	s_waitcnt lgkmcnt(6)
	global_store_dwordx4 v[40:41], v[46:49], off
	v_lshl_add_u64 v[40:41], v[40:41], 0, s[48:49]
	s_waitcnt lgkmcnt(5)
	global_store_dwordx4 v[40:41], v[50:53], off
	v_lshl_add_u64 v[40:41], v[40:41], 0, s[48:49]
	s_waitcnt lgkmcnt(4)
	global_store_dwordx4 v[40:41], v[54:57], off
	v_lshl_add_u64 v[40:41], v[40:41], 0, s[48:49]
	s_waitcnt lgkmcnt(3)
	global_store_dwordx4 v[40:41], v[58:61], off
	v_lshl_add_u64 v[40:41], v[40:41], 0, s[48:49]
	s_waitcnt lgkmcnt(2)
	global_store_dwordx4 v[40:41], v[62:65], off
	v_lshl_add_u64 v[40:41], v[40:41], 0, s[48:49]
	s_waitcnt lgkmcnt(1)
	global_store_dwordx4 v[40:41], v[66:69], off
	v_lshl_add_u64 v[40:41], v[40:41], 0, s[48:49]
	s_waitcnt lgkmcnt(0)
	global_store_dwordx4 v[40:41], v[70:73], off
	s_mov_b64 s[12:13], -1
	s_barrier
	s_cbranch_vccz .LBB0_598
